# v57 + nt (non-temporal) hint on the 76 streaming f32 loads of P0 (FFN1 weight transpose-copy and x row reads, each read once)
# speedup vs baseline: 1.0038x; 1.0038x over previous
.LBB0_14:
	s_cmpk_gt_i32 s28, 0x37ff
	s_mov_b64 s[6:7], -1
	s_cbranch_scc0 .LBB0_16
	s_and_b32 s2, 0xffff, s10
	s_mul_hi_u32 s2, s2, 0x124924a
	s_mul_i32 s42, s2, 0x3800
	s_sub_i32 s2, s9, s42
	s_and_b32 s2, s2, 0xffffff80
	s_mov_b32 s36, 6
	s_sub_i32 s35, s2, s42
	s_ashr_i32 s37, s36, 31
	s_add_i32 s6, s35, 0xfff200b8
	s_add_i32 s7, s35, 0xfff200b0
	s_add_i32 s29, s35, 0xfff200a8
	s_add_i32 s30, s35, 0xfff200a0
	s_add_i32 s31, s35, 0xfff20098
	s_add_i32 s33, s35, 0xfff20090
	s_add_i32 s34, s35, 0xfff20088
	s_add_i32 s35, s35, 0xfff20080
	s_lshl_b64 s[36:37], s[36:37], 3
	s_add_u32 s36, s70, s36
	s_addc_u32 s37, s71, s37
	s_load_dwordx2 s[38:39], s[36:37], 0x0
	s_mov_b32 s36, 3
	s_ashr_i32 s37, s36, 31
	s_lshl_b64 s[36:37], s[36:37], 3
	s_add_u32 s36, s70, s36
	s_addc_u32 s37, s71, s37
	s_add_i32 s2, s28, 0xc800
	s_bfe_u32 s2, s2, 0xb0005
	s_mulk_i32 s2, 0x2493
	v_mov_b32_e32 v84, v0
	s_lshr_b32 s2, s2, 16
	s_load_dwordx2 s[40:41], s[36:37], 0x0
	s_lshl_b32 s37, s2, 6
	s_add_i32 s36, s8, s27
	v_bfe_u32 v85, v84, 4, 2
	v_lshlrev_b32_e32 v2, 2, v84
	s_sub_i32 s42, s36, s42
	v_and_b32_e32 v86, 60, v2
	v_lshl_or_b32 v2, v85, 1, s37
	s_add_i32 s42, s42, 0xfff20000
	v_mul_u32_u24_e32 v2, 0xe000, v2
	s_waitcnt lgkmcnt(0)
	v_lshl_add_u64 v[4:5], s[38:39], 0, v[2:3]
	s_ashr_i32 s43, s42, 31
	v_lshl_add_u64 v[4:5], s[42:43], 2, v[4:5]
	v_lshlrev_b32_e32 v2, 2, v86
	v_lshl_add_u64 v[64:65], v[4:5], 0, v[2:3]
	v_add_co_u32_e32 v8, vcc, s11, v64
	s_lshl_b32 s37, s2, 8
	s_nop 0
	v_addc_co_u32_e32 v9, vcc, 0, v65, vcc
	v_add_co_u32_e32 v12, vcc, s12, v64
	s_add_u32 s38, s40, s37
	s_nop 0
	v_addc_co_u32_e32 v13, vcc, 0, v65, vcc
	v_add_co_u32_e32 v16, vcc, s13, v64
	s_addc_u32 s39, s41, 0
	s_nop 0
	v_addc_co_u32_e32 v17, vcc, 0, v65, vcc
	v_lshlrev_b32_e32 v2, 3, v85
	v_add_co_u32_e32 v20, vcc, s14, v64
	global_load_dwordx4 v[4:7], v[64:65], off nt
	global_load_dwordx2 v[68:69], v2, s[38:39]
	s_nop 0
	global_load_dwordx4 v[8:11], v[8:9], off nt
	v_addc_co_u32_e32 v21, vcc, 0, v65, vcc
	v_add_co_u32_e32 v24, vcc, s15, v64
	global_load_dwordx4 v[12:15], v[12:13], off nt
	s_nop 0
	v_addc_co_u32_e32 v25, vcc, 0, v65, vcc
	v_add_co_u32_e32 v28, vcc, s16, v64
	global_load_dwordx2 v[70:71], v2, s[38:39] offset:32
	s_nop 0
	v_addc_co_u32_e32 v29, vcc, 0, v65, vcc
	v_add_co_u32_e32 v32, vcc, s17, v64
	global_load_dwordx4 v[16:19], v[16:17], off nt
	s_nop 0
	global_load_dwordx4 v[20:23], v[20:21], off nt
	v_addc_co_u32_e32 v33, vcc, 0, v65, vcc
	v_add_co_u32_e32 v36, vcc, s18, v64
	global_load_dwordx2 v[72:73], v2, s[38:39] offset:64
	s_nop 0
	v_addc_co_u32_e32 v37, vcc, 0, v65, vcc
	v_add_co_u32_e32 v40, vcc, s19, v64
	global_load_dwordx4 v[24:27], v[24:25], off nt
	s_nop 0
	global_load_dwordx4 v[28:31], v[28:29], off nt
	v_addc_co_u32_e32 v41, vcc, 0, v65, vcc
	global_load_dwordx2 v[74:75], v2, s[38:39] offset:96
	v_add_co_u32_e32 v44, vcc, s20, v64
	global_load_dwordx4 v[32:35], v[32:33], off nt
	s_nop 0
	global_load_dwordx4 v[36:39], v[36:37], off nt
	v_addc_co_u32_e32 v45, vcc, 0, v65, vcc
	v_add_co_u32_e32 v48, vcc, s21, v64
	global_load_dwordx2 v[76:77], v2, s[38:39] offset:128
	s_nop 0
	v_addc_co_u32_e32 v49, vcc, 0, v65, vcc
	v_add_co_u32_e32 v52, vcc, s22, v64
	global_load_dwordx4 v[40:43], v[40:41], off nt
	s_nop 0
	global_load_dwordx4 v[44:47], v[44:45], off nt
	v_addc_co_u32_e32 v53, vcc, 0, v65, vcc
	global_load_dwordx2 v[78:79], v2, s[38:39] offset:160
	v_add_co_u32_e32 v56, vcc, s23, v64
	global_load_dwordx4 v[48:51], v[48:49], off nt
	s_nop 0
	global_load_dwordx4 v[52:55], v[52:53], off nt
	v_addc_co_u32_e32 v57, vcc, 0, v65, vcc
	v_add_co_u32_e32 v60, vcc, s24, v64
	global_load_dwordx2 v[80:81], v2, s[38:39] offset:192
	s_nop 0
	v_addc_co_u32_e32 v61, vcc, 0, v65, vcc
	v_add_co_u32_e32 v64, vcc, s25, v64
	global_load_dwordx4 v[56:59], v[56:57], off nt
	s_nop 0
	global_load_dwordx4 v[60:63], v[60:61], off nt
	v_addc_co_u32_e32 v65, vcc, 0, v65, vcc
	global_load_dwordx4 v[64:67], v[64:65], off nt
	s_nop 0
	global_load_dwordx2 v[82:83], v2, s[38:39] offset:224
	v_mul_u32_u24_e32 v2, 0x84, v86
	s_mulk_i32 s2, 0x7000
	s_waitcnt vmcnt(22)
	v_pk_mul_f32 v[4:5], v[4:5], v[68:69] op_sel_hi:[1,0]
	s_waitcnt vmcnt(21)
	v_pk_mul_f32 v[8:9], v[8:9], v[68:69] op_sel:[0,1]
	v_pk_mul_f32 v[6:7], v[6:7], v[68:69] op_sel_hi:[1,0]
	v_cvt_pk_bf16_f32 v4, v4, v8
	v_lshlrev_b32_e32 v8, 2, v85
	v_add3_u32 v2, s68, v2, v8
	ds_write_b32 v2, v4
	v_cvt_pk_bf16_f32 v4, v5, v9
	v_pk_mul_f32 v[10:11], v[10:11], v[68:69] op_sel:[0,1]
	ds_write_b32 v2, v4 offset:132
	v_cvt_pk_bf16_f32 v4, v6, v10
	ds_write_b32 v2, v4 offset:264
	v_cvt_pk_bf16_f32 v4, v7, v11
	s_waitcnt vmcnt(19)
	v_pk_mul_f32 v[6:7], v[12:13], v[70:71] op_sel_hi:[1,0]
	ds_write_b32 v2, v4 offset:396
	v_pk_mul_f32 v[4:5], v[14:15], v[70:71] op_sel_hi:[1,0]
	s_waitcnt vmcnt(18)
	v_pk_mul_f32 v[10:11], v[16:17], v[70:71] op_sel:[0,1]
	v_pk_mul_f32 v[8:9], v[18:19], v[70:71] op_sel:[0,1]
	v_cvt_pk_bf16_f32 v6, v6, v10
	ds_write_b32 v2, v6 offset:16
	v_cvt_pk_bf16_f32 v6, v7, v11
	ds_write_b32 v2, v6 offset:148
	v_cvt_pk_bf16_f32 v4, v4, v8
	ds_write_b32 v2, v4 offset:280
	v_cvt_pk_bf16_f32 v4, v5, v9
	s_waitcnt vmcnt(16)
	v_pk_mul_f32 v[6:7], v[20:21], v[72:73] op_sel_hi:[1,0]
	ds_write_b32 v2, v4 offset:412
	v_pk_mul_f32 v[4:5], v[22:23], v[72:73] op_sel_hi:[1,0]
	s_waitcnt vmcnt(15)
	v_pk_mul_f32 v[10:11], v[24:25], v[72:73] op_sel:[0,1]
	v_pk_mul_f32 v[8:9], v[26:27], v[72:73] op_sel:[0,1]
	v_cvt_pk_bf16_f32 v6, v6, v10
	ds_write_b32 v2, v6 offset:32
	v_cvt_pk_bf16_f32 v6, v7, v11
	ds_write_b32 v2, v6 offset:164
	v_cvt_pk_bf16_f32 v4, v4, v8
	ds_write_b32 v2, v4 offset:296
	v_cvt_pk_bf16_f32 v4, v5, v9
	s_waitcnt vmcnt(13)
	v_pk_mul_f32 v[6:7], v[28:29], v[74:75] op_sel_hi:[1,0]
	ds_write_b32 v2, v4 offset:428
	v_pk_mul_f32 v[4:5], v[30:31], v[74:75] op_sel_hi:[1,0]
	s_waitcnt vmcnt(12)
	v_pk_mul_f32 v[10:11], v[32:33], v[74:75] op_sel:[0,1]
	v_pk_mul_f32 v[8:9], v[34:35], v[74:75] op_sel:[0,1]
	v_cvt_pk_bf16_f32 v6, v6, v10
	ds_write_b32 v2, v6 offset:48
	v_cvt_pk_bf16_f32 v6, v7, v11
	ds_write_b32 v2, v6 offset:180
	v_cvt_pk_bf16_f32 v4, v4, v8
	ds_write_b32 v2, v4 offset:312
	v_cvt_pk_bf16_f32 v4, v5, v9
	s_waitcnt vmcnt(10)
	v_pk_mul_f32 v[6:7], v[36:37], v[76:77] op_sel_hi:[1,0]
	ds_write_b32 v2, v4 offset:444
	v_pk_mul_f32 v[4:5], v[38:39], v[76:77] op_sel_hi:[1,0]
	s_waitcnt vmcnt(9)
	v_pk_mul_f32 v[10:11], v[40:41], v[76:77] op_sel:[0,1]
	v_pk_mul_f32 v[8:9], v[42:43], v[76:77] op_sel:[0,1]
	v_cvt_pk_bf16_f32 v6, v6, v10
	ds_write_b32 v2, v6 offset:64
	v_cvt_pk_bf16_f32 v6, v7, v11
	ds_write_b32 v2, v6 offset:196
	v_cvt_pk_bf16_f32 v4, v4, v8
	ds_write_b32 v2, v4 offset:328
	v_cvt_pk_bf16_f32 v4, v5, v9
	s_waitcnt vmcnt(7)
	v_pk_mul_f32 v[6:7], v[44:45], v[78:79] op_sel_hi:[1,0]
	ds_write_b32 v2, v4 offset:460
	v_pk_mul_f32 v[4:5], v[46:47], v[78:79] op_sel_hi:[1,0]
	s_waitcnt vmcnt(6)
	v_pk_mul_f32 v[10:11], v[48:49], v[78:79] op_sel:[0,1]
	v_pk_mul_f32 v[8:9], v[50:51], v[78:79] op_sel:[0,1]
	v_cvt_pk_bf16_f32 v6, v6, v10
	ds_write_b32 v2, v6 offset:80
	v_cvt_pk_bf16_f32 v6, v7, v11
	ds_write_b32 v2, v6 offset:212
	v_cvt_pk_bf16_f32 v4, v4, v8
	ds_write_b32 v2, v4 offset:344
	v_cvt_pk_bf16_f32 v4, v5, v9
	s_waitcnt vmcnt(4)
	v_pk_mul_f32 v[6:7], v[52:53], v[80:81] op_sel_hi:[1,0]
	ds_write_b32 v2, v4 offset:476
	v_pk_mul_f32 v[4:5], v[54:55], v[80:81] op_sel_hi:[1,0]
	s_waitcnt vmcnt(3)
	v_pk_mul_f32 v[10:11], v[56:57], v[80:81] op_sel:[0,1]
	v_pk_mul_f32 v[8:9], v[58:59], v[80:81] op_sel:[0,1]
	v_cvt_pk_bf16_f32 v6, v6, v10
	ds_write_b32 v2, v6 offset:96
	v_cvt_pk_bf16_f32 v6, v7, v11
	ds_write_b32 v2, v6 offset:228
	v_cvt_pk_bf16_f32 v4, v4, v8
	ds_write_b32 v2, v4 offset:360
	v_cvt_pk_bf16_f32 v4, v5, v9
	s_waitcnt vmcnt(0)
	v_pk_mul_f32 v[6:7], v[60:61], v[82:83] op_sel_hi:[1,0]
	ds_write_b32 v2, v4 offset:492
	v_pk_mul_f32 v[4:5], v[62:63], v[82:83] op_sel_hi:[1,0]
	v_pk_mul_f32 v[10:11], v[64:65], v[82:83] op_sel:[0,1]
	v_pk_mul_f32 v[8:9], v[66:67], v[82:83] op_sel:[0,1]
	v_cvt_pk_bf16_f32 v6, v6, v10
	ds_write_b32 v2, v6 offset:112
	v_cvt_pk_bf16_f32 v6, v7, v11
	ds_write_b32 v2, v6 offset:244
	v_cvt_pk_bf16_f32 v4, v4, v8
	ds_write_b32 v2, v4 offset:376
	v_cvt_pk_bf16_f32 v4, v5, v9
	ds_write_b32 v2, v4 offset:508
	v_bfe_u32 v8, v84, 3, 3
	v_lshlrev_b32_e32 v2, 4, v84
	v_and_b32_e32 v2, 0x70, v2
	v_mul_u32_u24_e32 v4, 0x84, v8
	s_waitcnt lgkmcnt(0)
	v_lshl_add_u64 v[12:13], s[4:5], 0, v[2:3]
	v_add3_u32 v2, s68, v2, v4
	v_add_u32_e32 v16, s36, v8
	ds_read2_b32 v[4:5], v2 offset1:1
	ds_read2_b32 v[6:7], v2 offset0:2 offset1:3
	v_add_u32_e32 v8, s35, v16
	v_ashrrev_i32_e32 v9, 31, v8
	v_lshl_add_u64 v[8:9], s[2:3], 0, v[8:9]
	v_lshlrev_b64 v[8:9], 7, v[8:9]
	v_lshl_add_u64 v[14:15], v[12:13], 0, v[8:9]
	v_add_u32_e32 v8, 0x420, v2
	v_add_u32_e32 v10, 0x428, v2
	ds_read2_b32 v[8:9], v8 offset1:1
	ds_read2_b32 v[10:11], v10 offset1:1
	s_waitcnt lgkmcnt(2)
	global_store_dwordx4 v[14:15], v[4:7], off
	s_nop 1
	v_add_u32_e32 v4, s34, v16
	v_ashrrev_i32_e32 v5, 31, v4
	v_lshl_add_u64 v[4:5], s[2:3], 0, v[4:5]
	v_lshlrev_b64 v[4:5], 7, v[4:5]
	v_lshl_add_u64 v[4:5], v[12:13], 0, v[4:5]
	s_waitcnt lgkmcnt(0)
	global_store_dwordx4 v[4:5], v[8:11], off
	v_add_u32_e32 v4, 0x840, v2
	v_add_u32_e32 v6, 0x848, v2
	ds_read2_b32 v[4:5], v4 offset1:1
	ds_read2_b32 v[6:7], v6 offset1:1
	v_add_u32_e32 v8, s33, v16
	v_ashrrev_i32_e32 v9, 31, v8
	v_lshl_add_u64 v[8:9], s[2:3], 0, v[8:9]
	v_lshlrev_b64 v[8:9], 7, v[8:9]
	v_lshl_add_u64 v[14:15], v[12:13], 0, v[8:9]
	v_add_u32_e32 v8, 0xc60, v2
	v_add_u32_e32 v10, 0xc68, v2
	ds_read2_b32 v[8:9], v8 offset1:1
	ds_read2_b32 v[10:11], v10 offset1:1
	s_waitcnt lgkmcnt(2)
	global_store_dwordx4 v[14:15], v[4:7], off
	s_nop 1
	v_add_u32_e32 v4, s31, v16
	v_ashrrev_i32_e32 v5, 31, v4
	v_lshl_add_u64 v[4:5], s[2:3], 0, v[4:5]
	v_lshlrev_b64 v[4:5], 7, v[4:5]
	v_lshl_add_u64 v[4:5], v[12:13], 0, v[4:5]
	s_waitcnt lgkmcnt(0)
	global_store_dwordx4 v[4:5], v[8:11], off
	v_add_u32_e32 v4, 0x1080, v2
	v_add_u32_e32 v6, 0x1088, v2
	ds_read2_b32 v[4:5], v4 offset1:1
	ds_read2_b32 v[6:7], v6 offset1:1
	v_add_u32_e32 v8, s30, v16
	v_ashrrev_i32_e32 v9, 31, v8
	v_lshl_add_u64 v[8:9], s[2:3], 0, v[8:9]
	v_lshlrev_b64 v[8:9], 7, v[8:9]
	v_lshl_add_u64 v[14:15], v[12:13], 0, v[8:9]
	v_add_u32_e32 v8, 0x14a0, v2
	v_add_u32_e32 v10, 0x14a8, v2
	ds_read2_b32 v[8:9], v8 offset1:1
	ds_read2_b32 v[10:11], v10 offset1:1
	s_waitcnt lgkmcnt(2)
	global_store_dwordx4 v[14:15], v[4:7], off
	s_nop 1
	v_add_u32_e32 v4, s29, v16
	v_ashrrev_i32_e32 v5, 31, v4
	v_lshl_add_u64 v[4:5], s[2:3], 0, v[4:5]
	v_lshlrev_b64 v[4:5], 7, v[4:5]
	v_lshl_add_u64 v[4:5], v[12:13], 0, v[4:5]
	s_waitcnt lgkmcnt(0)
	global_store_dwordx4 v[4:5], v[8:11], off
	v_add_u32_e32 v4, 0x18c0, v2
	v_add_u32_e32 v6, 0x18c8, v2
	ds_read2_b32 v[4:5], v4 offset1:1
	ds_read2_b32 v[6:7], v6 offset1:1
	v_add_u32_e32 v8, s7, v16
	v_ashrrev_i32_e32 v9, 31, v8
	v_lshl_add_u64 v[8:9], s[2:3], 0, v[8:9]
	v_lshlrev_b64 v[8:9], 7, v[8:9]
	v_lshl_add_u64 v[14:15], v[12:13], 0, v[8:9]
	v_add_u32_e32 v8, 0x1ce0, v2
	v_add_u32_e32 v2, 0x1ce8, v2
	ds_read2_b32 v[8:9], v8 offset1:1
	ds_read2_b32 v[10:11], v2 offset1:1
	s_waitcnt lgkmcnt(2)
	global_store_dwordx4 v[14:15], v[4:7], off
	s_nop 1
	v_add_u32_e32 v4, s6, v16
	v_ashrrev_i32_e32 v5, 31, v4
	v_lshl_add_u64 v[4:5], s[2:3], 0, v[4:5]
	v_lshlrev_b64 v[4:5], 7, v[4:5]
	v_lshl_add_u64 v[4:5], v[12:13], 0, v[4:5]
	s_waitcnt lgkmcnt(0)
	global_store_dwordx4 v[4:5], v[8:11], off
	s_waitcnt lgkmcnt(0)
	s_mov_b64 s[6:7], 0
.LBB0_16:
	s_andn2_b64 vcc, exec, s[6:7]
	s_cbranch_vccnz .LBB0_13
	s_mov_b32 s6, 5
	s_ashr_i32 s7, s6, 31
	s_lshl_b64 s[6:7], s[6:7], 3
	s_add_u32 s6, s70, s6
	s_addc_u32 s7, s71, s7
	s_mov_b32 s30, 3
	s_load_dwordx2 s[6:7], s[6:7], 0x0
	s_ashr_i32 s31, s30, 31
	s_lshl_b64 s[30:31], s[30:31], 3
	s_add_u32 s30, s70, s30
	s_mul_hi_i32 s2, s28, 0x92492493
	s_addc_u32 s31, s71, s31
	s_add_i32 s2, s2, s28
	s_lshr_b32 s29, s2, 31
	s_ashr_i32 s2, s2, 7
	v_mov_b32_e32 v80, v0
	s_add_i32 s2, s2, s29
	s_load_dwordx2 s[30:31], s[30:31], 0x0
	s_lshl_b32 s34, s2, 6
	s_mul_i32 s33, s2, 0xffffc800
	s_add_i32 s29, s8, s27
	v_bfe_u32 v81, v80, 4, 2
	v_lshlrev_b32_e32 v2, 2, v80
	s_add_i32 s36, s29, s33
	v_and_b32_e32 v82, 60, v2
	v_lshl_or_b32 v2, v81, 1, s34
	s_waitcnt lgkmcnt(0)
	v_mov_b64_e32 v[4:5], s[6:7]
	v_mad_i64_i32 v[4:5], s[6:7], v2, s11, v[4:5]
	s_ashr_i32 s37, s36, 31
	v_lshl_add_u64 v[4:5], s[36:37], 2, v[4:5]
	v_lshlrev_b32_e32 v2, 2, v82
	v_lshl_add_u64 v[44:45], v[4:5], 0, v[2:3]
	s_ashr_i32 s35, s34, 31
	s_lshl_b64 s[6:7], s[34:35], 2
	v_add_co_u32_e32 v8, vcc, s11, v44
	s_add_u32 s6, s30, s6
	s_nop 0
	v_addc_co_u32_e32 v9, vcc, 0, v45, vcc
	s_addc_u32 s7, s31, s7
	v_lshlrev_b32_e32 v2, 3, v81
	global_load_dwordx4 v[4:7], v[44:45], off nt
	global_load_dwordx2 v[46:47], v2, s[6:7]
	v_add_co_u32_e32 v12, vcc, s12, v44
	global_load_dwordx4 v[8:11], v[8:9], off nt
	s_nop 0
	v_addc_co_u32_e32 v13, vcc, 0, v45, vcc
	v_add_co_u32_e32 v16, vcc, s13, v44
	global_load_dwordx4 v[12:15], v[12:13], off nt
	s_nop 0
	global_load_dwordx2 v[48:49], v2, s[6:7] offset:32
	v_addc_co_u32_e32 v17, vcc, 0, v45, vcc
	global_load_dwordx4 v[16:19], v[16:17], off nt
	v_add_co_u32_e32 v20, vcc, s14, v44
	v_mul_u32_u24_e32 v82, 0x84, v82
	s_nop 0
	v_addc_co_u32_e32 v21, vcc, 0, v45, vcc
	v_add_co_u32_e32 v24, vcc, s15, v44
	global_load_dwordx4 v[20:23], v[20:21], off nt
	s_nop 0
	global_load_dwordx2 v[52:53], v2, s[6:7] offset:64
	v_addc_co_u32_e32 v25, vcc, 0, v45, vcc
	global_load_dwordx4 v[24:27], v[24:25], off nt
	v_add_co_u32_e32 v28, vcc, s16, v44
	global_load_dwordx2 v[54:55], v2, s[6:7] offset:96
	s_nop 0
	v_addc_co_u32_e32 v29, vcc, 0, v45, vcc
	v_add_co_u32_e32 v32, vcc, s17, v44
	global_load_dwordx4 v[28:31], v[28:29], off nt
	s_nop 0
	v_addc_co_u32_e32 v33, vcc, 0, v45, vcc
	v_add_co_u32_e32 v50, vcc, s18, v44
	global_load_dwordx4 v[32:35], v[32:33], off nt
	s_nop 0
	v_addc_co_u32_e32 v51, vcc, 0, v45, vcc
	v_add_co_u32_e32 v56, vcc, s19, v44
	s_waitcnt vmcnt(10)
	v_pk_mul_f32 v[62:63], v[6:7], v[46:47] op_sel_hi:[1,0]
	v_addc_co_u32_e32 v57, vcc, 0, v45, vcc
	v_add_co_u32_e32 v58, vcc, s20, v44
	global_load_dwordx2 v[60:61], v2, s[6:7] offset:128
	global_load_dwordx4 v[36:39], v[50:51], off nt
	global_load_dwordx4 v[40:43], v[56:57], off nt
	v_addc_co_u32_e32 v59, vcc, 0, v45, vcc
	v_add_co_u32_e32 v50, vcc, s21, v44
	v_pk_mul_f32 v[64:65], v[4:5], v[46:47] op_sel_hi:[1,0]
	s_nop 0
	v_addc_co_u32_e32 v51, vcc, 0, v45, vcc
	v_add_co_u32_e32 v56, vcc, s22, v44
	global_load_dwordx2 v[68:69], v2, s[6:7] offset:160
	global_load_dwordx4 v[4:7], v[58:59], off nt
	v_addc_co_u32_e32 v57, vcc, 0, v45, vcc
	s_waitcnt vmcnt(14)
	v_pk_mul_f32 v[66:67], v[10:11], v[46:47] op_sel:[0,1]
	v_pk_mul_f32 v[58:59], v[8:9], v[46:47] op_sel:[0,1]
	global_load_dwordx4 v[8:11], v[50:51], off nt
	v_add_co_u32_e32 v46, vcc, s23, v44
	s_waitcnt vmcnt(13)
	v_pk_mul_f32 v[70:71], v[14:15], v[48:49] op_sel_hi:[1,0]
	v_addc_co_u32_e32 v47, vcc, 0, v45, vcc
	v_pk_mul_f32 v[72:73], v[12:13], v[48:49] op_sel_hi:[1,0]
	s_waitcnt vmcnt(12)
	v_pk_mul_f32 v[74:75], v[18:19], v[48:49] op_sel:[0,1]
	v_pk_mul_f32 v[76:77], v[16:17], v[48:49] op_sel:[0,1]
	global_load_dwordx2 v[78:79], v2, s[6:7] offset:192
	global_load_dwordx4 v[12:15], v[56:57], off nt
	global_load_dwordx4 v[16:19], v[46:47], off nt
	v_add_co_u32_e32 v46, vcc, s24, v44
	s_waitcnt vmcnt(13)
	v_pk_mul_f32 v[22:23], v[22:23], v[52:53] op_sel_hi:[1,0]
	v_addc_co_u32_e32 v47, vcc, 0, v45, vcc
	v_add_co_u32_e32 v48, vcc, s25, v44
	v_pk_mul_f32 v[20:21], v[20:21], v[52:53] op_sel_hi:[1,0]
	s_nop 0
	v_addc_co_u32_e32 v49, vcc, 0, v45, vcc
	global_load_dwordx2 v[56:57], v2, s[6:7] offset:224
	s_nop 0
	global_load_dwordx4 v[44:47], v[46:47], off nt
	v_lshlrev_b32_e32 v2, 2, v81
	global_load_dwordx4 v[48:51], v[48:49], off nt
	v_add3_u32 v2, s68, v82, v2
	s_waitcnt vmcnt(15)
	v_pk_mul_f32 v[26:27], v[26:27], v[52:53] op_sel:[0,1]
	v_pk_mul_f32 v[24:25], v[24:25], v[52:53] op_sel:[0,1]
	v_cvt_pk_bf16_f32 v52, v64, v58
	ds_write_b32 v2, v52
	v_cvt_pk_bf16_f32 v52, v65, v59
	ds_write_b32 v2, v52 offset:132
	v_cvt_pk_bf16_f32 v52, v62, v66
	ds_write_b32 v2, v52 offset:264
	v_cvt_pk_bf16_f32 v52, v63, v67
	ds_write_b32 v2, v52 offset:396
	v_cvt_pk_bf16_f32 v52, v72, v76
	ds_write_b32 v2, v52 offset:16
	v_cvt_pk_bf16_f32 v52, v73, v77
	ds_write_b32 v2, v52 offset:148
	v_cvt_pk_bf16_f32 v52, v70, v74
	ds_write_b32 v2, v52 offset:280
	v_cvt_pk_bf16_f32 v52, v71, v75
	ds_write_b32 v2, v52 offset:412
	v_cvt_pk_bf16_f32 v20, v20, v24
	ds_write_b32 v2, v20 offset:32
	v_cvt_pk_bf16_f32 v20, v21, v25
	ds_write_b32 v2, v20 offset:164
	v_cvt_pk_bf16_f32 v20, v22, v26
	ds_write_b32 v2, v20 offset:296
	v_cvt_pk_bf16_f32 v20, v23, v27
	s_waitcnt vmcnt(13)
	v_pk_mul_f32 v[22:23], v[28:29], v[54:55] op_sel_hi:[1,0]
	ds_write_b32 v2, v20 offset:428
	v_pk_mul_f32 v[20:21], v[30:31], v[54:55] op_sel_hi:[1,0]
	s_waitcnt vmcnt(12)
	v_pk_mul_f32 v[26:27], v[32:33], v[54:55] op_sel:[0,1]
	v_pk_mul_f32 v[24:25], v[34:35], v[54:55] op_sel:[0,1]
	v_cvt_pk_bf16_f32 v22, v22, v26
	ds_write_b32 v2, v22 offset:48
	v_cvt_pk_bf16_f32 v22, v23, v27
	ds_write_b32 v2, v22 offset:180
	v_cvt_pk_bf16_f32 v20, v20, v24
	ds_write_b32 v2, v20 offset:312
	v_cvt_pk_bf16_f32 v20, v21, v25
	ds_write_b32 v2, v20 offset:444
	s_mul_i32 s6, s2, 0x3800
	s_waitcnt vmcnt(10)
	v_pk_mul_f32 v[22:23], v[36:37], v[60:61] op_sel_hi:[1,0]
	v_pk_mul_f32 v[20:21], v[38:39], v[60:61] op_sel_hi:[1,0]
	s_waitcnt vmcnt(9)
	v_pk_mul_f32 v[26:27], v[40:41], v[60:61] op_sel:[0,1]
	v_pk_mul_f32 v[24:25], v[42:43], v[60:61] op_sel:[0,1]
	v_cvt_pk_bf16_f32 v22, v22, v26
	ds_write_b32 v2, v22 offset:64
	v_cvt_pk_bf16_f32 v22, v23, v27
	ds_write_b32 v2, v22 offset:196
	v_cvt_pk_bf16_f32 v20, v20, v24
	ds_write_b32 v2, v20 offset:328
	v_cvt_pk_bf16_f32 v20, v21, v25
	s_waitcnt vmcnt(7)
	v_pk_mul_f32 v[4:5], v[4:5], v[68:69] op_sel_hi:[1,0]
	ds_write_b32 v2, v20 offset:460
	v_pk_mul_f32 v[6:7], v[6:7], v[68:69] op_sel_hi:[1,0]
	s_waitcnt vmcnt(6)
	v_pk_mul_f32 v[8:9], v[8:9], v[68:69] op_sel:[0,1]
	s_nop 0
	v_cvt_pk_bf16_f32 v4, v4, v8
	ds_write_b32 v2, v4 offset:80
	v_cvt_pk_bf16_f32 v4, v5, v9
	v_pk_mul_f32 v[10:11], v[10:11], v[68:69] op_sel:[0,1]
	ds_write_b32 v2, v4 offset:212
	v_cvt_pk_bf16_f32 v4, v6, v10
	ds_write_b32 v2, v4 offset:344
	v_cvt_pk_bf16_f32 v4, v7, v11
	s_waitcnt vmcnt(4)
	v_pk_mul_f32 v[6:7], v[12:13], v[78:79] op_sel_hi:[1,0]
	ds_write_b32 v2, v4 offset:476
	v_pk_mul_f32 v[4:5], v[14:15], v[78:79] op_sel_hi:[1,0]
	s_waitcnt vmcnt(3)
	v_pk_mul_f32 v[10:11], v[16:17], v[78:79] op_sel:[0,1]
	v_pk_mul_f32 v[8:9], v[18:19], v[78:79] op_sel:[0,1]
	v_cvt_pk_bf16_f32 v6, v6, v10
	ds_write_b32 v2, v6 offset:96
	v_cvt_pk_bf16_f32 v6, v7, v11
	ds_write_b32 v2, v6 offset:228
	v_cvt_pk_bf16_f32 v4, v4, v8
	ds_write_b32 v2, v4 offset:360
	v_cvt_pk_bf16_f32 v4, v5, v9
	s_waitcnt vmcnt(1)
	v_pk_mul_f32 v[6:7], v[44:45], v[56:57] op_sel_hi:[1,0]
	ds_write_b32 v2, v4 offset:492
	v_pk_mul_f32 v[4:5], v[46:47], v[56:57] op_sel_hi:[1,0]
	s_waitcnt vmcnt(0)
	v_pk_mul_f32 v[10:11], v[48:49], v[56:57] op_sel:[0,1]
	v_pk_mul_f32 v[8:9], v[50:51], v[56:57] op_sel:[0,1]
	v_cvt_pk_bf16_f32 v6, v6, v10
	ds_write_b32 v2, v6 offset:112
	v_cvt_pk_bf16_f32 v6, v7, v11
	ds_write_b32 v2, v6 offset:244
	v_cvt_pk_bf16_f32 v4, v4, v8
	ds_write_b32 v2, v4 offset:376
	v_cvt_pk_bf16_f32 v4, v5, v9
	v_bfe_u32 v8, v80, 3, 3
	ds_write_b32 v2, v4 offset:508
	v_lshlrev_b32_e32 v2, 4, v80
	v_mul_u32_u24_e32 v4, 0x84, v8
	v_subrev_u32_e32 v8, s6, v8
	s_sub_i32 s6, s26, s6
	v_and_b32_e32 v2, 0x70, v2
	s_and_b32 s6, s6, 0xffffff80
	s_waitcnt lgkmcnt(0)
	v_lshl_add_u64 v[12:13], s[4:5], 0, v[2:3]
	v_add3_u32 v2, s68, v2, v4
	s_add_i32 s29, s29, s6
	ds_read2_b32 v[4:5], v2 offset1:1
	ds_read2_b32 v[6:7], v2 offset0:2 offset1:3
	v_add_u32_e32 v14, s29, v8
	v_ashrrev_i32_e32 v15, 31, v14
	v_mad_i64_i32 v[8:9], s[6:7], s2, v1, v[14:15]
	v_lshlrev_b64 v[8:9], 7, v[8:9]
	v_lshl_add_u64 v[16:17], v[12:13], 0, v[8:9]
	v_add_u32_e32 v8, 0x420, v2
	v_add_u32_e32 v10, 0x428, v2
	ds_read2_b32 v[8:9], v8 offset1:1
	ds_read2_b32 v[10:11], v10 offset1:1
	s_waitcnt lgkmcnt(2)
	global_store_dwordx4 v[16:17], v[4:7], off
	s_nop 1
	v_add_u32_e32 v4, 8, v14
	v_ashrrev_i32_e32 v5, 31, v4
	v_mad_i64_i32 v[4:5], s[6:7], s2, v1, v[4:5]
	v_lshlrev_b64 v[4:5], 7, v[4:5]
	v_lshl_add_u64 v[4:5], v[12:13], 0, v[4:5]
	s_waitcnt lgkmcnt(0)
	global_store_dwordx4 v[4:5], v[8:11], off
	v_add_u32_e32 v4, 0x840, v2
	v_add_u32_e32 v6, 0x848, v2
	ds_read2_b32 v[4:5], v4 offset1:1
	ds_read2_b32 v[6:7], v6 offset1:1
	v_add_u32_e32 v8, 16, v14
	v_ashrrev_i32_e32 v9, 31, v8
	v_mad_i64_i32 v[8:9], s[6:7], s2, v1, v[8:9]
	v_lshlrev_b64 v[8:9], 7, v[8:9]
	v_lshl_add_u64 v[16:17], v[12:13], 0, v[8:9]
	v_add_u32_e32 v8, 0xc60, v2
	v_add_u32_e32 v10, 0xc68, v2
	ds_read2_b32 v[8:9], v8 offset1:1
	ds_read2_b32 v[10:11], v10 offset1:1
	s_waitcnt lgkmcnt(2)
	global_store_dwordx4 v[16:17], v[4:7], off
	s_nop 1
	v_add_u32_e32 v4, 24, v14
	v_ashrrev_i32_e32 v5, 31, v4
	v_mad_i64_i32 v[4:5], s[6:7], s2, v1, v[4:5]
	v_lshlrev_b64 v[4:5], 7, v[4:5]
	v_lshl_add_u64 v[4:5], v[12:13], 0, v[4:5]
	s_waitcnt lgkmcnt(0)
	global_store_dwordx4 v[4:5], v[8:11], off
	v_add_u32_e32 v4, 0x1080, v2
	v_add_u32_e32 v6, 0x1088, v2
	ds_read2_b32 v[4:5], v4 offset1:1
	ds_read2_b32 v[6:7], v6 offset1:1
	v_add_u32_e32 v8, 32, v14
	v_ashrrev_i32_e32 v9, 31, v8
	v_mad_i64_i32 v[8:9], s[6:7], s2, v1, v[8:9]
	v_lshlrev_b64 v[8:9], 7, v[8:9]
	v_lshl_add_u64 v[16:17], v[12:13], 0, v[8:9]
	v_add_u32_e32 v8, 0x14a0, v2
	v_add_u32_e32 v10, 0x14a8, v2
	ds_read2_b32 v[8:9], v8 offset1:1
	ds_read2_b32 v[10:11], v10 offset1:1
	s_waitcnt lgkmcnt(2)
	global_store_dwordx4 v[16:17], v[4:7], off
	s_nop 1
	v_add_u32_e32 v4, 40, v14
	v_ashrrev_i32_e32 v5, 31, v4
	v_mad_i64_i32 v[4:5], s[6:7], s2, v1, v[4:5]
	v_lshlrev_b64 v[4:5], 7, v[4:5]
	v_lshl_add_u64 v[4:5], v[12:13], 0, v[4:5]
	s_waitcnt lgkmcnt(0)
	global_store_dwordx4 v[4:5], v[8:11], off
	v_add_u32_e32 v4, 0x18c0, v2
	v_add_u32_e32 v6, 0x18c8, v2
	ds_read2_b32 v[4:5], v4 offset1:1
	ds_read2_b32 v[6:7], v6 offset1:1
	v_add_u32_e32 v8, 48, v14
	v_ashrrev_i32_e32 v9, 31, v8
	v_mad_i64_i32 v[8:9], s[6:7], s2, v1, v[8:9]
	v_lshlrev_b64 v[8:9], 7, v[8:9]
	v_lshl_add_u64 v[16:17], v[12:13], 0, v[8:9]
	v_add_u32_e32 v8, 0x1ce0, v2
	v_add_u32_e32 v2, 0x1ce8, v2
	ds_read2_b32 v[8:9], v8 offset1:1
	ds_read2_b32 v[10:11], v2 offset1:1
	s_waitcnt lgkmcnt(2)
	global_store_dwordx4 v[16:17], v[4:7], off
	s_nop 1
	v_add_u32_e32 v4, 56, v14
	v_ashrrev_i32_e32 v5, 31, v4
	v_mad_i64_i32 v[4:5], s[6:7], s2, v1, v[4:5]
	v_lshlrev_b64 v[4:5], 7, v[4:5]
	v_lshl_add_u64 v[4:5], v[12:13], 0, v[4:5]
	s_waitcnt lgkmcnt(0)
	global_store_dwordx4 v[4:5], v[8:11], off
	s_waitcnt lgkmcnt(0)
	s_branch .LBB0_13

.LBB0_21:
	s_mov_b32 s14, 0
	s_ashr_i32 s15, s14, 31
	s_lshl_b64 s[14:15], s[14:15], 3
	s_add_u32 s14, s70, s14
	s_addc_u32 s15, s71, s15
	s_load_dwordx2 s[14:15], s[14:15], 0x0
	s_waitcnt lgkmcnt(0)
	v_lshl_add_u64 v[2:3], s[14:15], 0, v[70:71]
	v_add_co_u32_e32 v4, vcc, s16, v2
	global_load_dwordx4 v[62:65], v[2:3], off nt
	global_load_dwordx4 v[58:61], v[2:3], off offset:1024 nt
	global_load_dwordx4 v[54:57], v[2:3], off offset:2048 nt
	global_load_dwordx4 v[50:53], v[2:3], off offset:3072 nt
	v_addc_co_u32_e32 v5, vcc, 0, v3, vcc
	global_load_dwordx4 v[46:49], v[4:5], off offset:-4096 nt
	v_add_co_u32_e32 v6, vcc, s19, v2
	s_waitcnt vmcnt(4)
	v_mul_f32_e32 v81, v63, v63
	v_addc_co_u32_e32 v7, vcc, 0, v3, vcc
	global_load_dwordx4 v[42:45], v[6:7], off offset:1024 nt
	global_load_dwordx4 v[38:41], v[6:7], off offset:2048 nt
	global_load_dwordx4 v[34:37], v[6:7], off offset:3072 nt
	global_load_dwordx4 v[30:33], v[4:5], off nt
	global_load_dwordx4 v[26:29], v[4:5], off offset:1024 nt
	global_load_dwordx4 v[22:25], v[4:5], off offset:2048 nt
	global_load_dwordx4 v[18:21], v[4:5], off offset:3072 nt
	v_add_co_u32_e32 v82, vcc, s20, v2
	s_waitcnt vmcnt(10)
	v_mul_f32_e32 v84, v61, v61
	v_addc_co_u32_e32 v83, vcc, 0, v3, vcc
	global_load_dwordx4 v[14:17], v[82:83], off nt
	global_load_dwordx4 v[10:13], v[82:83], off offset:1024 nt
	global_load_dwordx4 v[6:9], v[82:83], off offset:2048 nt
	global_load_dwordx4 v[2:5], v[82:83], off offset:3072 nt
	v_mul_f32_e32 v82, v65, v65
	v_mul_f32_e32 v83, v59, v59
	s_waitcnt vmcnt(13)
	v_mul_f32_e32 v85, v55, v55
	v_mul_f32_e32 v86, v57, v57
	v_fmac_f32_e32 v81, v62, v62
	v_fmac_f32_e32 v82, v64, v64
	v_fmac_f32_e32 v83, v58, v58
	v_fmac_f32_e32 v84, v60, v60
	s_waitcnt vmcnt(12)
	v_mul_f32_e32 v87, v51, v51
	v_mul_f32_e32 v88, v53, v53
	v_fmac_f32_e32 v85, v54, v54
	v_fmac_f32_e32 v86, v56, v56
	v_add_f32_e32 v81, v81, v82
	v_add_f32_e32 v82, v83, v84
	v_fmac_f32_e32 v87, v50, v50
	v_fmac_f32_e32 v88, v52, v52
	s_waitcnt vmcnt(11)
	v_mul_f32_e32 v89, v47, v47
	v_mul_f32_e32 v90, v49, v49
	v_add_f32_e32 v83, v85, v86
	v_add_f32_e32 v81, v81, v82
	v_add_f32_e32 v84, v87, v88
	v_fmac_f32_e32 v89, v46, v46
	v_fmac_f32_e32 v90, v48, v48
	v_add_f32_e32 v81, v81, v83
	v_add_f32_e32 v82, v89, v90
	v_add_f32_e32 v81, v81, v84
	v_add_f32_e32 v81, v81, v82
	v_cmp_lt_i32_e32 vcc, v74, v73
	s_waitcnt vmcnt(10)
	v_mul_f32_e32 v91, v43, v43
	v_mul_f32_e32 v92, v45, v45
	s_waitcnt vmcnt(9)
	v_mul_f32_e32 v93, v39, v39
	v_mul_f32_e32 v94, v41, v41
	v_fmac_f32_e32 v91, v42, v42
	v_fmac_f32_e32 v92, v44, v44
	s_waitcnt vmcnt(8)
	v_mul_f32_e32 v95, v35, v35
	v_mul_f32_e32 v96, v37, v37
	v_fmac_f32_e32 v93, v38, v38
	v_fmac_f32_e32 v94, v40, v40
	v_add_f32_e32 v89, v91, v92
	v_fmac_f32_e32 v95, v34, v34
	v_fmac_f32_e32 v96, v36, v36
	s_waitcnt vmcnt(7)
	v_mul_f32_e32 v85, v31, v31
	v_mul_f32_e32 v86, v33, v33
	v_add_f32_e32 v90, v93, v94
	v_add_f32_e32 v81, v81, v89
	s_waitcnt vmcnt(6)
	v_mul_f32_e32 v87, v27, v27
	v_mul_f32_e32 v88, v29, v29
	v_add_f32_e32 v91, v95, v96
	v_fmac_f32_e32 v85, v30, v30
	v_fmac_f32_e32 v86, v32, v32
	v_add_f32_e32 v81, v81, v90
	s_waitcnt vmcnt(5)
	v_mul_f32_e32 v97, v23, v23
	v_mul_f32_e32 v98, v25, v25
	v_fmac_f32_e32 v87, v26, v26
	v_fmac_f32_e32 v88, v28, v28
	v_add_f32_e32 v83, v85, v86
	v_add_f32_e32 v81, v81, v91
	s_waitcnt vmcnt(4)
	v_mul_f32_e32 v99, v19, v19
	v_mul_f32_e32 v100, v21, v21
	v_fmac_f32_e32 v97, v22, v22
	v_fmac_f32_e32 v98, v24, v24
	v_add_f32_e32 v85, v87, v88
	v_add_f32_e32 v81, v81, v83
	v_fmac_f32_e32 v99, v18, v18
	v_add_f32_e32 v86, v97, v98
	v_add_f32_e32 v81, v81, v85
	v_fmac_f32_e32 v100, v20, v20
	v_add_f32_e32 v81, v81, v86
	v_add_f32_e32 v82, v99, v100
	v_add_f32_e32 v81, v81, v82
	s_waitcnt vmcnt(3)
	v_mul_f32_e32 v82, v15, v15
	v_mul_f32_e32 v83, v17, v17
	v_fmac_f32_e32 v82, v14, v14
	v_fmac_f32_e32 v83, v16, v16
	v_add_f32_e32 v82, v82, v83
	v_add_f32_e32 v81, v81, v82
	s_waitcnt vmcnt(2)
	v_mul_f32_e32 v82, v11, v11
	v_mul_f32_e32 v83, v13, v13
	v_fmac_f32_e32 v82, v10, v10
	v_fmac_f32_e32 v83, v12, v12
	v_add_f32_e32 v82, v82, v83
	v_add_f32_e32 v81, v81, v82
	s_waitcnt vmcnt(1)
	v_mul_f32_e32 v82, v7, v7
	v_mul_f32_e32 v83, v9, v9
	v_fmac_f32_e32 v82, v6, v6
	v_fmac_f32_e32 v83, v8, v8
	v_add_f32_e32 v82, v82, v83
	v_add_f32_e32 v81, v81, v82
	s_waitcnt vmcnt(0)
	v_mul_f32_e32 v82, v3, v3
	v_mul_f32_e32 v83, v5, v5
	v_fmac_f32_e32 v82, v2, v2
	v_fmac_f32_e32 v83, v4, v4
	v_add_f32_e32 v82, v82, v83
	v_add_f32_e32 v81, v81, v82
	v_cndmask_b32_e32 v82, v66, v74, vcc
	v_lshlrev_b32_e32 v82, 2, v82
	ds_bpermute_b32 v82, v82, v81
	v_cmp_lt_i32_e32 vcc, v75, v73
	s_waitcnt lgkmcnt(0)
	v_add_f32_e32 v81, v81, v82
	v_cndmask_b32_e32 v82, v66, v75, vcc
	v_lshlrev_b32_e32 v82, 2, v82
	ds_bpermute_b32 v82, v82, v81
	v_cmp_lt_i32_e32 vcc, v76, v73
	s_waitcnt lgkmcnt(0)
	v_add_f32_e32 v81, v81, v82
	v_cndmask_b32_e32 v82, v66, v76, vcc
	v_lshlrev_b32_e32 v82, 2, v82
	ds_bpermute_b32 v82, v82, v81
	v_cmp_lt_i32_e32 vcc, v77, v73
	s_waitcnt lgkmcnt(0)
	v_add_f32_e32 v81, v81, v82
	v_cndmask_b32_e32 v82, v66, v77, vcc
	v_lshlrev_b32_e32 v82, 2, v82
	ds_bpermute_b32 v82, v82, v81
	v_cmp_lt_i32_e32 vcc, v78, v73
	s_waitcnt lgkmcnt(0)
	v_add_f32_e32 v81, v81, v82
	v_cndmask_b32_e32 v82, v66, v78, vcc
	v_lshlrev_b32_e32 v82, 2, v82
	ds_bpermute_b32 v82, v82, v81
	v_cmp_lt_i32_e32 vcc, v79, v73
	s_waitcnt lgkmcnt(0)
	v_add_f32_e32 v81, v81, v82
	v_cndmask_b32_e32 v82, v66, v79, vcc
	v_lshlrev_b32_e32 v82, 2, v82
	ds_bpermute_b32 v82, v82, v81
	s_and_saveexec_b64 s[14:15], s[6:7]
	s_cbranch_execz .LBB0_20
	s_waitcnt lgkmcnt(0)
	v_add_f32_e32 v81, v81, v82
	v_fmamk_f32 v81, v81, 0x39800000, v80
	v_rsq_f32_e32 v81, v81
	s_add_u32 s22, s72, s17
	s_addc_u32 s23, s73, s18
	global_store_dword v67, v81, s[22:23]
	s_branch .LBB0_20

.LBB0_25:
	s_mov_b32 s8, 1
	v_cmp_lt_i32_e32 vcc, v101, v100
	s_ashr_i32 s9, s8, 31
	s_lshl_b64 s[8:9], s[8:9], 3
	v_cndmask_b32_e32 v2, v91, v101, vcc
	v_cmp_lt_i32_e32 vcc, v102, v100
	s_add_u32 s8, s70, s8
	s_addc_u32 s9, s71, s9
	v_cndmask_b32_e32 v3, v91, v102, vcc
	v_cmp_lt_i32_e32 vcc, v103, v100
	s_load_dwordx2 s[8:9], s[8:9], 0x0
	s_mov_b32 s10, 20
	v_cndmask_b32_e32 v4, v91, v103, vcc
	v_cmp_lt_i32_e32 vcc, v104, v100
	s_ashr_i32 s11, s10, 31
	s_lshl_b64 s[10:11], s[10:11], 3
	v_cndmask_b32_e32 v5, v91, v104, vcc
	v_cmp_lt_i32_e32 vcc, v105, v100
	s_add_u32 s10, s70, s10
	v_lshlrev_b32_e32 v145, 2, v2
	v_cndmask_b32_e32 v6, v91, v105, vcc
	v_cmp_lt_i32_e32 vcc, v106, v100
	v_lshlrev_b32_e32 v147, 2, v3
	s_addc_u32 s11, s71, s11
	v_cndmask_b32_e32 v7, v91, v106, vcc
	v_add_co_u32_e32 v92, vcc, s17, v84
	s_waitcnt lgkmcnt(0)
	v_lshl_add_u64 v[2:3], s[8:9], 0, v[86:87]
	v_addc_co_u32_e32 v93, vcc, 0, v85, vcc
	v_add_co_u32_e32 v94, vcc, s18, v84
	s_load_dwordx2 s[10:11], s[10:11], 0x0
	s_nop 0
	v_addc_co_u32_e32 v95, vcc, 0, v85, vcc
	v_add_co_u32_e32 v98, vcc, s19, v84
	global_load_dwordx4 v[62:65], v[2:3], off nt
	global_load_dwordx4 v[58:61], v[2:3], off offset:1024 nt
	global_load_dwordx4 v[54:57], v[2:3], off offset:2048 nt
	global_load_dwordx4 v[50:53], v[2:3], off offset:3072 nt
	v_addc_co_u32_e32 v99, vcc, 0, v85, vcc
	v_lshlrev_b32_e32 v148, 2, v4
	v_add_co_u32_e32 v4, vcc, s14, v2
	v_lshlrev_b32_e32 v149, 2, v5
	s_nop 0
	v_addc_co_u32_e32 v5, vcc, 0, v3, vcc
	v_add_co_u32_e32 v66, vcc, s15, v2
	v_lshlrev_b32_e32 v150, 2, v6
	s_nop 0
	v_addc_co_u32_e32 v67, vcc, 0, v3, vcc
	global_load_dwordx4 v[42:45], v[66:67], off offset:-4096 nt
	global_load_dwordx4 v[34:37], v[4:5], off offset:2048 nt
	global_load_dwordx4 v[46:49], v[4:5], off offset:1024 nt
	global_load_dwordx4 v[38:41], v[4:5], off offset:3072 nt
	v_add_co_u32_e32 v68, vcc, s16, v2
	v_lshlrev_b32_e32 v151, 2, v7
	s_nop 0
	v_addc_co_u32_e32 v69, vcc, 0, v3, vcc
	global_load_dwordx4 v[18:21], v[66:67], off offset:1024 nt
	global_load_dwordx4 v[30:33], v[66:67], off nt
	global_load_dwordx4 v[22:25], v[66:67], off offset:2048 nt
	global_load_dwordx4 v[6:9], v[68:69], off nt
	global_load_dwordx4 v[26:29], v[66:67], off offset:3072 nt
	global_load_dwordx4 v[10:13], v[68:69], off offset:1024 nt
	global_load_dwordx4 v[2:5], v[68:69], off offset:3072 nt
	global_load_dwordx4 v[14:17], v[68:69], off offset:2048 nt
	s_waitcnt lgkmcnt(0)
	global_load_dwordx4 v[78:81], v82, s[10:11]
	global_load_dwordx4 v[74:77], v82, s[10:11] offset:1024
	global_load_dwordx4 v[70:73], v82, s[10:11] offset:2048
	global_load_dwordx4 v[66:69], v82, s[10:11] offset:3072
	v_lshl_add_u64 v[88:89], s[10:11], 0, v[82:83]
	v_add_co_u32_e32 v108, vcc, s14, v88
	s_add_i32 s31, s31, s76
	s_nop 0
	v_addc_co_u32_e32 v109, vcc, 0, v89, vcc
	v_add_co_u32_e32 v96, vcc, s15, v88
	v_lshl_add_u64 v[86:87], v[86:87], 0, s[6:7]
	s_nop 0
	v_addc_co_u32_e32 v97, vcc, 0, v89, vcc
	s_cmpk_gt_i32 s31, 0xff
	s_waitcnt vmcnt(19)
	v_pk_mul_f32 v[110:111], v[64:65], v[64:65]
	v_pk_mul_f32 v[112:113], v[62:63], v[62:63]
	s_waitcnt vmcnt(18)
	v_pk_mul_f32 v[114:115], v[60:61], v[60:61]
	v_pk_mul_f32 v[116:117], v[58:59], v[58:59]
	v_pk_mov_b32 v[120:121], v[112:113], v[110:111] op_sel:[1,0]
	v_mov_b32_e32 v113, v111
	v_pk_mov_b32 v[110:111], v[116:117], v[114:115] op_sel:[1,0]
	v_mov_b32_e32 v117, v115
	s_waitcnt vmcnt(17)
	v_mul_f32_e32 v90, v55, v55
	v_mul_f32_e32 v118, v57, v57
	v_pk_add_f32 v[112:113], v[120:121], v[112:113]
	v_pk_add_f32 v[110:111], v[110:111], v[116:117]
	s_waitcnt vmcnt(16)
	v_mul_f32_e32 v152, v50, v50
	v_mul_f32_e32 v153, v51, v51
	v_mul_f32_e32 v127, v52, v52
	v_mul_f32_e32 v132, v53, v53
	v_pk_fma_f32 v[114:115], v[54:55], v[54:55], v[90:91] op_sel_hi:[1,1,0]
	v_pk_fma_f32 v[118:119], v[56:57], v[56:57], v[118:119] op_sel_hi:[1,1,0]
	v_pk_add_f32 v[112:113], v[112:113], v[112:113] op_sel:[0,1] op_sel_hi:[1,0]
	v_pk_add_f32 v[110:111], v[110:111], v[110:111] op_sel:[0,1] op_sel_hi:[1,0]
	s_waitcnt vmcnt(15)
	v_pk_mul_f32 v[122:123], v[44:45], v[44:45]
	v_pk_mul_f32 v[124:125], v[42:43], v[42:43]
	v_mov_b32_e32 v115, v127
	v_mov_b32_e32 v119, v132
	v_mov_b32_e32 v113, v152
	v_mov_b32_e32 v111, v153
	v_pk_mov_b32 v[116:117], v[124:125], v[122:123] op_sel:[1,0]
	v_mov_b32_e32 v125, v123
	v_pk_add_f32 v[114:115], v[114:115], v[118:119]
	v_pk_add_f32 v[110:111], v[112:113], v[110:111]
	s_waitcnt vmcnt(13)
	v_mul_f32_e32 v90, v47, v47
	v_mul_f32_e32 v126, v49, v49
	v_pk_add_f32 v[116:117], v[116:117], v[124:125]
	v_pk_add_f32 v[110:111], v[110:111], v[114:115]
	v_mul_f32_e32 v154, v34, v34
	v_mul_f32_e32 v155, v35, v35
	v_mul_f32_e32 v137, v36, v36
	v_mul_f32_e32 v139, v37, v37
	v_pk_fma_f32 v[120:121], v[46:47], v[46:47], v[90:91] op_sel_hi:[1,1,0]
	v_pk_fma_f32 v[122:123], v[48:49], v[48:49], v[126:127] op_sel_hi:[1,1,0]
	v_pk_add_f32 v[116:117], v[116:117], v[116:117] op_sel:[0,1] op_sel_hi:[1,0]
	v_pk_add_f32 v[110:111], v[110:111], v[110:111] op_sel:[0,1] op_sel_hi:[1,0]
	s_waitcnt vmcnt(12)
	v_pk_mul_f32 v[128:129], v[40:41], v[40:41]
	v_pk_mul_f32 v[130:131], v[38:39], v[38:39]
	v_mov_b32_e32 v121, v137
	v_mov_b32_e32 v123, v139
	v_mov_b32_e32 v117, v155
	v_mov_b32_e32 v111, v154
	v_pk_mov_b32 v[126:127], v[130:131], v[128:129] op_sel:[1,0]
	v_mov_b32_e32 v131, v129
	v_pk_add_f32 v[120:121], v[120:121], v[122:123]
	v_pk_add_f32 v[110:111], v[110:111], v[116:117]
	s_waitcnt vmcnt(10)
	v_mul_f32_e32 v90, v31, v31
	v_mul_f32_e32 v128, v33, v33
	v_pk_add_f32 v[118:119], v[126:127], v[130:131]
	v_pk_add_f32 v[110:111], v[110:111], v[120:121]
	v_mul_f32_e32 v156, v18, v18
	v_mul_f32_e32 v157, v19, v19
	v_mul_f32_e32 v158, v20, v20
	v_mul_f32_e32 v159, v21, v21
	v_pk_fma_f32 v[124:125], v[30:31], v[30:31], v[90:91] op_sel_hi:[1,1,0]
	v_pk_fma_f32 v[126:127], v[32:33], v[32:33], v[128:129] op_sel_hi:[1,1,0]
	v_pk_add_f32 v[118:119], v[118:119], v[118:119] op_sel:[0,1] op_sel_hi:[1,0]
	v_pk_add_f32 v[110:111], v[110:111], v[110:111] op_sel:[0,1] op_sel_hi:[1,0]
	s_waitcnt vmcnt(9)
	v_pk_mul_f32 v[132:133], v[24:25], v[24:25]
	v_pk_mul_f32 v[134:135], v[22:23], v[22:23]
	v_mov_b32_e32 v125, v158
	v_mov_b32_e32 v127, v159
	v_mov_b32_e32 v119, v157
	v_mov_b32_e32 v111, v156
	v_pk_mov_b32 v[128:129], v[134:135], v[132:133] op_sel:[1,0]
	v_mov_b32_e32 v135, v133
	v_pk_add_f32 v[112:113], v[124:125], v[126:127]
	v_pk_add_f32 v[110:111], v[110:111], v[118:119]
	s_waitcnt vmcnt(7)
	v_mul_f32_e32 v136, v27, v27
	v_mul_f32_e32 v138, v29, v29
	v_pk_add_f32 v[122:123], v[128:129], v[134:135]
	v_pk_add_f32 v[110:111], v[110:111], v[112:113]
	v_mul_f32_e32 v160, v6, v6
	v_mul_f32_e32 v161, v7, v7
	v_mul_f32_e32 v162, v8, v8
	v_mul_f32_e32 v163, v9, v9
	v_pk_fma_f32 v[130:131], v[26:27], v[26:27], v[136:137] op_sel_hi:[1,1,0]
	v_pk_fma_f32 v[132:133], v[28:29], v[28:29], v[138:139] op_sel_hi:[1,1,0]
	v_pk_add_f32 v[122:123], v[122:123], v[122:123] op_sel:[0,1] op_sel_hi:[1,0]
	v_pk_add_f32 v[110:111], v[110:111], v[110:111] op_sel:[0,1] op_sel_hi:[1,0]
	s_waitcnt vmcnt(6)
	v_pk_mul_f32 v[140:141], v[12:13], v[12:13]
	v_pk_mul_f32 v[142:143], v[10:11], v[10:11]
	v_mov_b32_e32 v131, v162
	v_mov_b32_e32 v133, v163
	v_mov_b32_e32 v123, v161
	v_mov_b32_e32 v111, v160
	v_pk_mov_b32 v[136:137], v[142:143], v[140:141] op_sel:[1,0]
	v_mov_b32_e32 v143, v141
	v_pk_add_f32 v[124:125], v[130:131], v[132:133]
	v_pk_add_f32 v[110:111], v[110:111], v[122:123]
	s_waitcnt vmcnt(4)
	v_mul_f32_e32 v144, v15, v15
	v_mul_f32_e32 v146, v17, v17
	v_pk_add_f32 v[128:129], v[136:137], v[142:143]
	v_pk_add_f32 v[110:111], v[110:111], v[124:125]
	v_mul_f32_e32 v164, v2, v2
	v_mul_f32_e32 v165, v3, v3
	v_mul_f32_e32 v166, v4, v4
	v_mul_f32_e32 v167, v5, v5
	v_pk_fma_f32 v[138:139], v[14:15], v[14:15], v[144:145] op_sel_hi:[1,1,0]
	v_pk_fma_f32 v[140:141], v[16:17], v[16:17], v[146:147] op_sel_hi:[1,1,0]
	v_pk_add_f32 v[126:127], v[128:129], v[128:129] op_sel:[0,1] op_sel_hi:[1,0]
	v_pk_add_f32 v[110:111], v[110:111], v[110:111] op_sel:[0,1] op_sel_hi:[1,0]
	v_mov_b32_e32 v139, v166
	v_mov_b32_e32 v141, v167
	v_mov_b32_e32 v127, v165
	v_mov_b32_e32 v111, v164
	v_pk_add_f32 v[128:129], v[138:139], v[140:141]
	v_pk_add_f32 v[110:111], v[110:111], v[126:127]
	s_nop 0
	v_pk_add_f32 v[110:111], v[110:111], v[128:129]
	s_nop 0
	v_add_f32_e32 v90, v110, v111
	ds_bpermute_b32 v110, v145, v90
	s_waitcnt lgkmcnt(0)
	v_add_f32_e32 v90, v90, v110
	ds_bpermute_b32 v110, v147, v90
	s_waitcnt lgkmcnt(0)
	v_add_f32_e32 v90, v90, v110
	ds_bpermute_b32 v110, v148, v90
	s_waitcnt lgkmcnt(0)
	v_add_f32_e32 v90, v90, v110
	ds_bpermute_b32 v110, v149, v90
	s_waitcnt lgkmcnt(0)
	v_add_f32_e32 v90, v90, v110
	ds_bpermute_b32 v110, v150, v90
	s_waitcnt lgkmcnt(0)
	v_add_f32_e32 v90, v90, v110
	ds_bpermute_b32 v110, v151, v90
	s_waitcnt lgkmcnt(0)
	v_add_f32_e32 v90, v90, v110
	v_fmamk_f32 v90, v90, 0x39800000, v107
	v_rsq_f32_e32 v90, v90
	s_nop 0
	v_pk_mul_f32 v[62:63], v[62:63], v[90:91] op_sel_hi:[1,0]
	v_pk_mul_f32 v[58:59], v[58:59], v[90:91] op_sel_hi:[1,0]
	v_pk_mul_f32 v[54:55], v[54:55], v[90:91] op_sel_hi:[1,0]
	v_pk_mul_f32 v[50:51], v[50:51], v[90:91] op_sel_hi:[1,0]
	v_pk_mul_f32 v[64:65], v[64:65], v[90:91] op_sel_hi:[1,0]
	v_pk_mul_f32 v[60:61], v[60:61], v[90:91] op_sel_hi:[1,0]
	v_pk_mul_f32 v[56:57], v[56:57], v[90:91] op_sel_hi:[1,0]
	v_pk_mul_f32 v[52:53], v[52:53], v[90:91] op_sel_hi:[1,0]
	s_waitcnt vmcnt(3)
	v_pk_mul_f32 v[62:63], v[78:79], v[62:63]
	s_waitcnt vmcnt(2)
	v_pk_mul_f32 v[58:59], v[74:75], v[58:59]
	s_waitcnt vmcnt(1)
	v_pk_mul_f32 v[54:55], v[70:71], v[54:55]
	s_waitcnt vmcnt(0)
	v_pk_mul_f32 v[50:51], v[66:67], v[50:51]
	v_pk_mul_f32 v[64:65], v[80:81], v[64:65]
	v_pk_mul_f32 v[60:61], v[76:77], v[60:61]
	v_pk_mul_f32 v[56:57], v[72:73], v[56:57]
	v_pk_mul_f32 v[52:53], v[68:69], v[52:53]
	v_cvt_pk_bf16_f32 v62, v62, v63
	v_cvt_pk_bf16_f32 v63, v64, v65
	global_store_dwordx2 v[84:85], v[62:63], off
	v_cvt_pk_bf16_f32 v58, v58, v59
	v_cvt_pk_bf16_f32 v59, v60, v61
	global_store_dwordx2 v[92:93], v[58:59], off
	v_cvt_pk_bf16_f32 v54, v54, v55
	v_cvt_pk_bf16_f32 v55, v56, v57
	global_store_dwordx2 v[94:95], v[54:55], off
	v_cvt_pk_bf16_f32 v50, v50, v51
	v_cvt_pk_bf16_f32 v51, v52, v53
	global_store_dwordx2 v[98:99], v[50:51], off
	global_load_dwordx4 v[50:53], v[96:97], off offset:-4096 nt
	global_load_dwordx4 v[54:57], v[108:109], off offset:1024 nt
	global_load_dwordx4 v[58:61], v[108:109], off offset:2048 nt
	global_load_dwordx4 v[62:65], v[108:109], off offset:3072 nt
	v_add_co_u32_e32 v66, vcc, s20, v84
	v_pk_mul_f32 v[42:43], v[42:43], v[90:91] op_sel_hi:[1,0]
	s_nop 0
	v_addc_co_u32_e32 v67, vcc, 0, v85, vcc
	v_add_co_u32_e32 v68, vcc, s21, v84
	v_pk_mul_f32 v[44:45], v[44:45], v[90:91] op_sel_hi:[1,0]
	s_nop 0
	v_addc_co_u32_e32 v69, vcc, 0, v85, vcc
	v_add_co_u32_e32 v70, vcc, s22, v84
	v_pk_mul_f32 v[34:35], v[34:35], v[90:91] op_sel_hi:[1,0]
	s_nop 0
	v_addc_co_u32_e32 v71, vcc, 0, v85, vcc
	v_add_co_u32_e32 v72, vcc, s23, v84
	v_pk_mul_f32 v[46:47], v[46:47], v[90:91] op_sel_hi:[1,0]
	v_pk_mul_f32 v[48:49], v[48:49], v[90:91] op_sel_hi:[1,0]
	v_pk_mul_f32 v[36:37], v[36:37], v[90:91] op_sel_hi:[1,0]
	v_addc_co_u32_e32 v73, vcc, 0, v85, vcc
	v_pk_mul_f32 v[38:39], v[38:39], v[90:91] op_sel_hi:[1,0]
	v_pk_mul_f32 v[40:41], v[40:41], v[90:91] op_sel_hi:[1,0]
	v_pk_mul_f32 v[30:31], v[30:31], v[90:91] op_sel_hi:[1,0]
	v_pk_mul_f32 v[18:19], v[18:19], v[90:91] op_sel_hi:[1,0]
	v_pk_mul_f32 v[32:33], v[32:33], v[90:91] op_sel_hi:[1,0]
	v_pk_mul_f32 v[20:21], v[20:21], v[90:91] op_sel_hi:[1,0]
	v_pk_mul_f32 v[22:23], v[22:23], v[90:91] op_sel_hi:[1,0]
	v_pk_mul_f32 v[24:25], v[24:25], v[90:91] op_sel_hi:[1,0]
	v_pk_mul_f32 v[26:27], v[26:27], v[90:91] op_sel_hi:[1,0]
	v_pk_mul_f32 v[28:29], v[28:29], v[90:91] op_sel_hi:[1,0]
	v_pk_mul_f32 v[6:7], v[6:7], v[90:91] op_sel_hi:[1,0]
	v_pk_mul_f32 v[8:9], v[8:9], v[90:91] op_sel_hi:[1,0]
	v_pk_mul_f32 v[10:11], v[10:11], v[90:91] op_sel_hi:[1,0]
	v_pk_mul_f32 v[12:13], v[12:13], v[90:91] op_sel_hi:[1,0]
	v_pk_mul_f32 v[2:3], v[2:3], v[90:91] op_sel_hi:[1,0]
	v_pk_mul_f32 v[14:15], v[14:15], v[90:91] op_sel_hi:[1,0]
	v_pk_mul_f32 v[16:17], v[16:17], v[90:91] op_sel_hi:[1,0]
	v_pk_mul_f32 v[4:5], v[4:5], v[90:91] op_sel_hi:[1,0]
	s_waitcnt vmcnt(3)
	v_pk_mul_f32 v[42:43], v[42:43], v[50:51]
	v_pk_mul_f32 v[44:45], v[44:45], v[52:53]
	s_waitcnt vmcnt(1)
	v_pk_mul_f32 v[34:35], v[34:35], v[58:59]
	v_cvt_pk_bf16_f32 v42, v42, v43
	v_cvt_pk_bf16_f32 v43, v44, v45
	v_pk_mul_f32 v[48:49], v[48:49], v[56:57]
	v_pk_mul_f32 v[46:47], v[46:47], v[54:55]
	v_pk_mul_f32 v[36:37], v[36:37], v[60:61]
	global_store_dwordx2 v[66:67], v[42:43], off
	v_cvt_pk_bf16_f32 v42, v46, v47
	v_cvt_pk_bf16_f32 v43, v48, v49
	global_store_dwordx2 v[68:69], v[42:43], off
	v_cvt_pk_bf16_f32 v34, v34, v35
	v_cvt_pk_bf16_f32 v35, v36, v37
	s_waitcnt vmcnt(2)
	v_pk_mul_f32 v[40:41], v[40:41], v[64:65]
	v_pk_mul_f32 v[38:39], v[38:39], v[62:63]
	global_store_dwordx2 v[70:71], v[34:35], off
	v_cvt_pk_bf16_f32 v34, v38, v39
	v_cvt_pk_bf16_f32 v35, v40, v41
	global_store_dwordx2 v[72:73], v[34:35], off
	global_load_dwordx4 v[34:37], v[96:97], off nt
	global_load_dwordx4 v[38:41], v[96:97], off offset:1024 nt
	global_load_dwordx4 v[42:45], v[96:97], off offset:2048 nt
	global_load_dwordx4 v[46:49], v[96:97], off offset:3072 nt
	v_add_co_u32_e32 v50, vcc, s24, v84
	s_waitcnt vmcnt(3)
	v_pk_mul_f32 v[30:31], v[30:31], v[34:35]
	v_addc_co_u32_e32 v51, vcc, 0, v85, vcc
	v_add_co_u32_e32 v52, vcc, s25, v84
	s_waitcnt vmcnt(2)
	v_pk_mul_f32 v[18:19], v[18:19], v[38:39]
	v_addc_co_u32_e32 v53, vcc, 0, v85, vcc
	v_add_co_u32_e32 v54, vcc, s26, v84
	v_pk_mul_f32 v[32:33], v[32:33], v[36:37]
	s_nop 0
	v_addc_co_u32_e32 v55, vcc, 0, v85, vcc
	v_add_co_u32_e32 v56, vcc, s27, v84
	v_pk_mul_f32 v[20:21], v[20:21], v[40:41]
	v_cvt_pk_bf16_f32 v30, v30, v31
	v_cvt_pk_bf16_f32 v31, v32, v33
	global_store_dwordx2 v[50:51], v[30:31], off
	v_cvt_pk_bf16_f32 v18, v18, v19
	v_cvt_pk_bf16_f32 v19, v20, v21
	v_addc_co_u32_e32 v57, vcc, 0, v85, vcc
	s_waitcnt vmcnt(2)
	v_pk_mul_f32 v[24:25], v[24:25], v[44:45]
	v_pk_mul_f32 v[22:23], v[22:23], v[42:43]
	global_store_dwordx2 v[52:53], v[18:19], off
	v_cvt_pk_bf16_f32 v18, v22, v23
	v_cvt_pk_bf16_f32 v19, v24, v25
	v_add_co_u32_e32 v58, vcc, s16, v88
	s_waitcnt vmcnt(2)
	v_pk_mul_f32 v[28:29], v[28:29], v[48:49]
	v_pk_mul_f32 v[26:27], v[26:27], v[46:47]
	global_store_dwordx2 v[54:55], v[18:19], off
	v_cvt_pk_bf16_f32 v18, v26, v27
	v_cvt_pk_bf16_f32 v19, v28, v29
	global_store_dwordx2 v[56:57], v[18:19], off
	v_addc_co_u32_e32 v59, vcc, 0, v89, vcc
	global_load_dwordx4 v[18:21], v[58:59], off nt
	global_load_dwordx4 v[22:25], v[58:59], off offset:1024 nt
	global_load_dwordx4 v[26:29], v[58:59], off offset:2048 nt
	global_load_dwordx4 v[30:33], v[58:59], off offset:3072 nt
	v_add_co_u32_e32 v34, vcc, s28, v84
	s_waitcnt vmcnt(3)
	v_pk_mul_f32 v[6:7], v[6:7], v[18:19]
	v_addc_co_u32_e32 v35, vcc, 0, v85, vcc
	v_add_co_u32_e32 v36, vcc, s29, v84
	v_pk_mul_f32 v[8:9], v[8:9], v[20:21]
	s_nop 0
	v_addc_co_u32_e32 v37, vcc, 0, v85, vcc
	v_add_co_u32_e32 v38, vcc, s30, v84
	v_cvt_pk_bf16_f32 v6, v6, v7
	v_cvt_pk_bf16_f32 v7, v8, v9
	s_waitcnt vmcnt(2)
	v_pk_mul_f32 v[12:13], v[12:13], v[24:25]
	v_addc_co_u32_e32 v39, vcc, 0, v85, vcc
	v_add_co_u32_e32 v40, vcc, 0x1e0000, v84
	v_pk_mul_f32 v[10:11], v[10:11], v[22:23]
	s_nop 0
	v_addc_co_u32_e32 v41, vcc, 0, v85, vcc
	s_waitcnt vmcnt(0)
	v_pk_mul_f32 v[2:3], v[2:3], v[30:31]
	global_store_dwordx2 v[34:35], v[6:7], off
	v_cvt_pk_bf16_f32 v6, v10, v11
	v_cvt_pk_bf16_f32 v7, v12, v13
	v_pk_mul_f32 v[16:17], v[16:17], v[28:29]
	v_pk_mul_f32 v[14:15], v[14:15], v[26:27]
	v_pk_mul_f32 v[4:5], v[4:5], v[32:33]
	global_store_dwordx2 v[36:37], v[6:7], off
	v_cvt_pk_bf16_f32 v6, v14, v15
	v_cvt_pk_bf16_f32 v7, v16, v17
	global_store_dwordx2 v[38:39], v[6:7], off
	v_cvt_pk_bf16_f32 v2, v2, v3
	v_cvt_pk_bf16_f32 v3, v4, v5
	global_store_dwordx2 v[40:41], v[2:3], off
	v_lshl_add_u64 v[84:85], v[84:85], 0, s[2:3]
	s_cbranch_scc0 .LBB0_25
